# X39: X38 plus the down loop's A-operand loads also in scalar-base form (their lane offset is a 32-bit value)
# speedup vs baseline: 1.0062x; 1.0023x over previous
; #define PG8_STAGE(bufoff, gbase, voff) do { _Pragma("unroll") for (int _i = 0; _i < 2; ++_i) \
;         __builtin_amdgcn_global_load_lds((const unsigned*)((const char*)(gbase) + (voff)[_i]), (PG8_LAS unsigned*)(lds + (bufoff) + ldsw + _i * 8192), 16, 0, 0); } while (0)
; #define PG8_LDA(dst, b, h) do { _Pragma("unroll") for (int m = 0; m < 4; ++m) _Pragma("unroll") for (int k = 0; k < 2; ++k) dst[m][k] = *(const PG8_LAS bf16x8*)(lds + PG8_SA(b, h) + aoff + m * 2048 + k * 1024); } while (0)
; #define PG8_LDB(dst, b, h) do { _Pragma("unroll") for (int n = 0; n < 2; ++n) _Pragma("unroll") for (int k = 0; k < 2; ++k) dst[n][k] = *(const PG8_LAS bf16x8*)(lds + PG8_SB(b, h) + boff + n * 2048 + k * 1024); } while (0)
; #define PG8_WAIT_V(n) asm volatile("s_waitcnt vmcnt(" #n ")" ::: "memory")
; #define PG8_WAIT_L(n) asm volatile("s_waitcnt lgkmcnt(" #n ")" ::: "memory")
; #define PG8_BAR __builtin_amdgcn_s_barrier()
; #define PG8_SCHED __builtin_amdgcn_sched_barrier(0)
; template <class Epi, class Sched, bool ALIGN_EPI = false, bool SP2 = false>
; __device__ __forceinline__ void gemm_phase(PG8_LAS unsigned char* lds, const Gemm g, const Sched& S, const Epi& E) {
;     ...
;         for (int t = 0; t < nt; t += 2) {
;             const bool last = (t == nt - 2);
;             const char* a1 = cA + (size_t)(t + 1) * kstep;
;             const char* a2 = last ? nA : cA + (size_t)(t + 2) * kstep; const char* b2 = last ? nB : cB + (size_t)(t + 2) * kstep;
;             const char* a3 = a2 + kstep; const char* b3 = b2 + kstep;
;             if (last && has_next) S.a_ready(nxt);
;             if constexpr (SP2) {
;             PG8_LDB(B0, 0, 0); PG8_LDB(B1, 0, 1); PG8_SCHED; PG8_LDA(At, 0, 0); PG8_STAGE(PG8_SA(1, 1), a1 + hstep, voffA);
;             PG8_WAIT_V(8); PG8_WAIT_L(0); PG8_BAR; PG8_MMA(0, 0, At, B0); PG8_MMA(0, 1, At, B1); PG8_BAR; PG8_SCHED;
;             PG8_LDA(At, 0, 1); PG8_STAGE(PG8_SB(0, 0), b2, voffB); PG8_STAGE(PG8_SB(0, 1), b2 + hstep, voffB); PG8_STAGE(PG8_SA(0, 0), a2, voffA);
;             PG8_WAIT_V(8); PG8_WAIT_L(0); PG8_BAR; PG8_MMA(1, 0, At, B0); PG8_MMA(1, 1, At, B1); PG8_BAR; PG8_SCHED;
;             PG8_LDB(B0, 1, 0); PG8_LDB(B1, 1, 1); PG8_SCHED; PG8_LDA(At, 1, 0); PG8_STAGE(PG8_SA(0, 1), a2 + hstep, voffA);
;             PG8_WAIT_V(8); PG8_WAIT_L(0); PG8_BAR; PG8_MMA(0, 0, At, B0); PG8_MMA(0, 1, At, B1); PG8_BAR; PG8_SCHED;
.LBB0_298:
	s_add_u32 s33, s50, 0x100
	s_addc_u32 s69, s51, 0
	s_mov_b32 s20, -2
	v_add_u32_e32 v236, 0x10000, v158
	v_add_u32_e32 v237, 0x14000, v158
	v_add_u32_e32 v238, 0x18000, v158
	v_add_u32_e32 v239, 0x1c000, v158
.LBB0_299:
	s_add_u32 s50, s22, 0x100
	s_addc_u32 s51, s23, 0
	s_add_i32 s4, 0, 0x10000
	s_cmpk_eq_i32 s20, 0x54
	s_cselect_b32 s55, s41, s51
	s_cselect_b32 s54, s40, s50
	s_cselect_b32 s53, s49, s69
	s_cselect_b32 s52, s48, s33
	s_add_i32 s5, 0, 0x14000
	ds_read_b128 v[134:137], v236
	ds_read_b128 v[138:141], v236 offset:1024
	ds_read_b128 v[142:145], v236 offset:2048
	ds_read_b128 v[146:149], v236 offset:3072
	ds_read_b128 v[150:153], v237
	ds_read_b128 v[154:157], v237 offset:1024
	ds_read_b128 v[176:179], v237 offset:2048
	ds_read_b128 v[180:183], v237 offset:3072
	s_add_i32 m0, s56, 0xc000
	ds_read_b128 v[184:187], v188
	ds_read_b128 v[190:193], v188 offset:1024
	ds_read_b128 v[212:215], v188 offset:2048
	ds_read_b128 v[216:219], v188 offset:3072
	ds_read_b128 v[220:223], v188 offset:4096
	ds_read_b128 v[224:227], v188 offset:5120
	ds_read_b128 v[228:231], v188 offset:6144
	ds_read_b128 v[232:235], v188 offset:7168
	global_load_lds_dwordx4 v172, s[22:23]
	s_add_i32 m0, s56, 0xe000
	s_nop 0
	global_load_lds_dwordx4 v174, s[22:23]
	s_waitcnt vmcnt(8)
	s_waitcnt lgkmcnt(0)
	s_barrier
	v_mfma_f32_16x16x32_bf16 v[122:125], v[134:137], v[184:187], v[122:125]
	v_mfma_f32_16x16x32_bf16 v[122:125], v[138:141], v[190:193], v[122:125]
	v_mfma_f32_16x16x32_bf16 v[118:121], v[142:145], v[184:187], v[118:121]
	v_mfma_f32_16x16x32_bf16 v[118:121], v[146:149], v[190:193], v[118:121]
	v_mfma_f32_16x16x32_bf16 v[130:133], v[150:153], v[184:187], v[130:133]
	v_mfma_f32_16x16x32_bf16 v[130:133], v[154:157], v[190:193], v[130:133]
	v_mfma_f32_16x16x32_bf16 v[126:129], v[176:179], v[184:187], v[126:129]
	v_mfma_f32_16x16x32_bf16 v[126:129], v[180:183], v[190:193], v[126:129]
	v_mfma_f32_16x16x32_bf16 v[102:105], v[176:179], v[212:215], v[102:105]
	v_mfma_f32_16x16x32_bf16 v[102:105], v[180:183], v[216:219], v[102:105]
	v_mfma_f32_16x16x32_bf16 v[106:109], v[150:153], v[212:215], v[106:109]
	v_mfma_f32_16x16x32_bf16 v[106:109], v[154:157], v[216:219], v[106:109]
	v_mfma_f32_16x16x32_bf16 v[110:113], v[142:145], v[212:215], v[110:113]
	v_mfma_f32_16x16x32_bf16 v[110:113], v[146:149], v[216:219], v[110:113]
	v_mfma_f32_16x16x32_bf16 v[114:117], v[134:137], v[212:215], v[114:117]
	v_mfma_f32_16x16x32_bf16 v[114:117], v[138:141], v[216:219], v[114:117]
	v_mfma_f32_16x16x32_bf16 v[98:101], v[134:137], v[220:223], v[98:101]
	v_mfma_f32_16x16x32_bf16 v[98:101], v[138:141], v[224:227], v[98:101]
	v_mfma_f32_16x16x32_bf16 v[94:97], v[142:145], v[220:223], v[94:97]
	v_mfma_f32_16x16x32_bf16 v[94:97], v[146:149], v[224:227], v[94:97]
	v_mfma_f32_16x16x32_bf16 v[90:93], v[150:153], v[220:223], v[90:93]
	v_mfma_f32_16x16x32_bf16 v[90:93], v[154:157], v[224:227], v[90:93]
	v_mfma_f32_16x16x32_bf16 v[86:89], v[176:179], v[220:223], v[86:89]
	v_mfma_f32_16x16x32_bf16 v[86:89], v[180:183], v[224:227], v[86:89]
	v_mfma_f32_16x16x32_bf16 v[70:73], v[176:179], v[228:231], v[70:73]
	v_mfma_f32_16x16x32_bf16 v[70:73], v[180:183], v[232:235], v[70:73]
	v_mfma_f32_16x16x32_bf16 v[74:77], v[150:153], v[228:231], v[74:77]
	v_mfma_f32_16x16x32_bf16 v[74:77], v[154:157], v[232:235], v[74:77]
	v_mfma_f32_16x16x32_bf16 v[78:81], v[142:145], v[228:231], v[78:81]
	v_mfma_f32_16x16x32_bf16 v[78:81], v[146:149], v[232:235], v[78:81]
	v_mfma_f32_16x16x32_bf16 v[82:85], v[134:137], v[228:231], v[82:85]
	v_mfma_f32_16x16x32_bf16 v[82:85], v[138:141], v[232:235], v[82:85]
	s_barrier
	s_add_i32 s4, s4, s24
	s_mov_b32 m0, s4
	ds_read_b128 v[184:187], v188 offset:16384
	ds_read_b128 v[190:193], v188 offset:17408
	ds_read_b128 v[212:215], v188 offset:18432
	ds_read_b128 v[216:219], v188 offset:19456
	ds_read_b128 v[220:223], v188 offset:20480
	ds_read_b128 v[224:227], v188 offset:21504
	ds_read_b128 v[228:231], v188 offset:22528
	ds_read_b128 v[232:235], v188 offset:23552
	global_load_lds_dwordx4 v4, s[52:53]
	s_add_i32 m0, s4, 0x2000
	s_add_u32 s22, s52, 0x160000
	s_addc_u32 s23, s53, 0
	s_add_i32 s4, s5, s24
	global_load_lds_dwordx4 v170, s[52:53]
	s_mov_b32 m0, s4
	s_nop 0
	global_load_lds_dwordx4 v4, s[22:23]
	s_add_i32 m0, s4, 0x2000
	s_nop 0
	global_load_lds_dwordx4 v170, s[22:23]
	s_mov_b32 m0, s56
	s_nop 0
	global_load_lds_dwordx4 v2, s[54:55]
	s_mov_b32 m0, s57
	s_nop 0
	global_load_lds_dwordx4 v168, s[54:55]
	s_waitcnt vmcnt(8)
	s_waitcnt lgkmcnt(0)
	s_barrier
	v_mfma_f32_16x16x32_bf16 v[58:61], v[134:137], v[184:187], v[58:61]
	v_mfma_f32_16x16x32_bf16 v[58:61], v[138:141], v[190:193], v[58:61]
	v_mfma_f32_16x16x32_bf16 v[54:57], v[142:145], v[184:187], v[54:57]
	v_mfma_f32_16x16x32_bf16 v[54:57], v[146:149], v[190:193], v[54:57]
	v_mfma_f32_16x16x32_bf16 v[66:69], v[150:153], v[184:187], v[66:69]
	v_mfma_f32_16x16x32_bf16 v[66:69], v[154:157], v[190:193], v[66:69]
	v_mfma_f32_16x16x32_bf16 v[62:65], v[176:179], v[184:187], v[62:65]
	v_mfma_f32_16x16x32_bf16 v[62:65], v[180:183], v[190:193], v[62:65]
	v_mfma_f32_16x16x32_bf16 v[38:41], v[176:179], v[212:215], v[38:41]
	v_mfma_f32_16x16x32_bf16 v[38:41], v[180:183], v[216:219], v[38:41]
	v_mfma_f32_16x16x32_bf16 v[42:45], v[150:153], v[212:215], v[42:45]
	v_mfma_f32_16x16x32_bf16 v[42:45], v[154:157], v[216:219], v[42:45]
	v_mfma_f32_16x16x32_bf16 v[46:49], v[142:145], v[212:215], v[46:49]
	v_mfma_f32_16x16x32_bf16 v[46:49], v[146:149], v[216:219], v[46:49]
	v_mfma_f32_16x16x32_bf16 v[50:53], v[134:137], v[212:215], v[50:53]
	v_mfma_f32_16x16x32_bf16 v[50:53], v[138:141], v[216:219], v[50:53]
	v_mfma_f32_16x16x32_bf16 v[34:37], v[134:137], v[220:223], v[34:37]
	v_mfma_f32_16x16x32_bf16 v[34:37], v[138:141], v[224:227], v[34:37]
	v_mfma_f32_16x16x32_bf16 v[30:33], v[142:145], v[220:223], v[30:33]
	v_mfma_f32_16x16x32_bf16 v[30:33], v[146:149], v[224:227], v[30:33]
	v_mfma_f32_16x16x32_bf16 v[26:29], v[150:153], v[220:223], v[26:29]
	v_mfma_f32_16x16x32_bf16 v[26:29], v[154:157], v[224:227], v[26:29]
	v_mfma_f32_16x16x32_bf16 v[22:25], v[176:179], v[220:223], v[22:25]
	v_mfma_f32_16x16x32_bf16 v[22:25], v[180:183], v[224:227], v[22:25]
	v_mfma_f32_16x16x32_bf16 v[6:9], v[176:179], v[228:231], v[6:9]
	v_mfma_f32_16x16x32_bf16 v[6:9], v[180:183], v[232:235], v[6:9]
	v_mfma_f32_16x16x32_bf16 v[10:13], v[150:153], v[228:231], v[10:13]
	v_mfma_f32_16x16x32_bf16 v[10:13], v[154:157], v[232:235], v[10:13]
	v_mfma_f32_16x16x32_bf16 v[14:17], v[142:145], v[228:231], v[14:17]
	v_mfma_f32_16x16x32_bf16 v[14:17], v[146:149], v[232:235], v[14:17]
	v_mfma_f32_16x16x32_bf16 v[18:21], v[134:137], v[228:231], v[18:21]
	v_mfma_f32_16x16x32_bf16 v[18:21], v[138:141], v[232:235], v[18:21]
	s_barrier
; #define PG8_STAGE(bufoff, gbase, voff) do { _Pragma("unroll") for (int _i = 0; _i < 2; ++_i) \
;         __builtin_amdgcn_global_load_lds((const unsigned*)((const char*)(gbase) + (voff)[_i]), (PG8_LAS unsigned*)(lds + (bufoff) + ldsw + _i * 8192), 16, 0, 0); } while (0)
; #define PG8_LDA(dst, b, h) do { _Pragma("unroll") for (int m = 0; m < 4; ++m) _Pragma("unroll") for (int k = 0; k < 2; ++k) dst[m][k] = *(const PG8_LAS bf16x8*)(lds + PG8_SA(b, h) + aoff + m * 2048 + k * 1024); } while (0)
; #define PG8_LDB(dst, b, h) do { _Pragma("unroll") for (int n = 0; n < 2; ++n) _Pragma("unroll") for (int k = 0; k < 2; ++k) dst[n][k] = *(const PG8_LAS bf16x8*)(lds + PG8_SB(b, h) + boff + n * 2048 + k * 1024); } while (0)
; #define PG8_MMA(ai, bj, At, Bt) do { __builtin_amdgcn_s_setprio(1); _Pragma("unroll") for (int m = 0; m < 4; ++m) _Pragma("unroll") for (int n = 0; n < 2; ++n) _Pragma("unroll") for (int k = 0; k < 2; ++k) \
;         acc[ai][bj][m][n] = __builtin_amdgcn_mfma_f32_16x16x32_bf16(Bt[n][k], At[m][k], acc[ai][bj][m][n], 0, 0, 0); __builtin_amdgcn_s_setprio(0); } while (0)
; #define PG8_WAIT_V(n) asm volatile("s_waitcnt vmcnt(" #n ")" ::: "memory")
; #define PG8_WAIT_L(n) asm volatile("s_waitcnt lgkmcnt(" #n ")" ::: "memory")
; #define PG8_BAR __builtin_amdgcn_s_barrier()
; #define PG8_SCHED __builtin_amdgcn_sched_barrier(0)
; template <class Epi, class Sched, bool ALIGN_EPI = false, bool SP2 = false>
; __device__ __forceinline__ void gemm_phase(PG8_LAS unsigned char* lds, const Gemm g, const Sched& S, const Epi& E) {
;     ...
;         for (int t = 0; t < nt; t += 2) {
;     ...
;             PG8_WAIT_V(8); PG8_WAIT_L(0); PG8_BAR; PG8_MMA(1, 0, At, B0); PG8_MMA(1, 1, At, B1); PG8_BAR; PG8_SCHED;
;             PG8_LDB(B0, 1, 0); PG8_LDB(B1, 1, 1); PG8_SCHED; PG8_LDA(At, 1, 0); PG8_STAGE(PG8_SA(0, 1), a2 + hstep, voffA);
;             PG8_WAIT_V(8); PG8_WAIT_L(0); PG8_BAR; PG8_MMA(0, 0, At, B0); PG8_MMA(0, 1, At, B1); PG8_BAR; PG8_SCHED;
;             PG8_LDA(At, 1, 1); PG8_STAGE(PG8_SB(1, 0), b3, voffB); PG8_STAGE(PG8_SB(1, 1), b3 + hstep, voffB); PG8_STAGE(PG8_SA(1, 0), a3, voffA);
;             PG8_WAIT_V(8); PG8_WAIT_L(0); PG8_BAR; PG8_MMA(1, 0, At, B0); PG8_MMA(1, 1, At, B1); PG8_BAR; PG8_SCHED;
	s_add_i32 s4, 0, 0x18000
	s_add_i32 s5, 0, 0x1c000
	ds_read_b128 v[134:137], v238
	ds_read_b128 v[138:141], v238 offset:1024
	ds_read_b128 v[142:145], v238 offset:2048
	ds_read_b128 v[146:149], v238 offset:3072
	ds_read_b128 v[150:153], v239
	ds_read_b128 v[154:157], v239 offset:1024
	ds_read_b128 v[176:179], v239 offset:2048
	ds_read_b128 v[180:183], v239 offset:3072
	s_add_u32 s22, s54, 0x160000
	s_addc_u32 s23, s55, 0
	s_mov_b32 m0, s59
	ds_read_b128 v[184:187], v188 offset:32768
	ds_read_b128 v[190:193], v188 offset:33792
	ds_read_b128 v[212:215], v188 offset:34816
	ds_read_b128 v[216:219], v188 offset:35840
	ds_read_b128 v[220:223], v188 offset:36864
	ds_read_b128 v[224:227], v188 offset:37888
	ds_read_b128 v[228:231], v188 offset:38912
	ds_read_b128 v[232:235], v188 offset:39936
	global_load_lds_dwordx4 v2, s[22:23]
	s_mov_b32 m0, s60
	s_nop 0
	global_load_lds_dwordx4 v168, s[22:23]
	s_waitcnt vmcnt(8)
	s_waitcnt lgkmcnt(0)
	s_barrier
	v_mfma_f32_16x16x32_bf16 v[122:125], v[134:137], v[184:187], v[122:125]
	v_mfma_f32_16x16x32_bf16 v[122:125], v[138:141], v[190:193], v[122:125]
	v_mfma_f32_16x16x32_bf16 v[118:121], v[142:145], v[184:187], v[118:121]
	v_mfma_f32_16x16x32_bf16 v[118:121], v[146:149], v[190:193], v[118:121]
	v_mfma_f32_16x16x32_bf16 v[130:133], v[150:153], v[184:187], v[130:133]
	v_mfma_f32_16x16x32_bf16 v[130:133], v[154:157], v[190:193], v[130:133]
	v_mfma_f32_16x16x32_bf16 v[126:129], v[176:179], v[184:187], v[126:129]
	v_mfma_f32_16x16x32_bf16 v[126:129], v[180:183], v[190:193], v[126:129]
	v_mfma_f32_16x16x32_bf16 v[102:105], v[176:179], v[212:215], v[102:105]
	v_mfma_f32_16x16x32_bf16 v[102:105], v[180:183], v[216:219], v[102:105]
	v_mfma_f32_16x16x32_bf16 v[106:109], v[150:153], v[212:215], v[106:109]
	v_mfma_f32_16x16x32_bf16 v[106:109], v[154:157], v[216:219], v[106:109]
	v_mfma_f32_16x16x32_bf16 v[110:113], v[142:145], v[212:215], v[110:113]
	v_mfma_f32_16x16x32_bf16 v[110:113], v[146:149], v[216:219], v[110:113]
	v_mfma_f32_16x16x32_bf16 v[114:117], v[134:137], v[212:215], v[114:117]
	v_mfma_f32_16x16x32_bf16 v[114:117], v[138:141], v[216:219], v[114:117]
	v_mfma_f32_16x16x32_bf16 v[98:101], v[134:137], v[220:223], v[98:101]
	v_mfma_f32_16x16x32_bf16 v[98:101], v[138:141], v[224:227], v[98:101]
	v_mfma_f32_16x16x32_bf16 v[94:97], v[142:145], v[220:223], v[94:97]
	v_mfma_f32_16x16x32_bf16 v[94:97], v[146:149], v[224:227], v[94:97]
	v_mfma_f32_16x16x32_bf16 v[90:93], v[150:153], v[220:223], v[90:93]
	v_mfma_f32_16x16x32_bf16 v[90:93], v[154:157], v[224:227], v[90:93]
	v_mfma_f32_16x16x32_bf16 v[86:89], v[176:179], v[220:223], v[86:89]
	v_mfma_f32_16x16x32_bf16 v[86:89], v[180:183], v[224:227], v[86:89]
	v_mfma_f32_16x16x32_bf16 v[70:73], v[176:179], v[228:231], v[70:73]
	v_mfma_f32_16x16x32_bf16 v[70:73], v[180:183], v[232:235], v[70:73]
	v_mfma_f32_16x16x32_bf16 v[74:77], v[150:153], v[228:231], v[74:77]
	v_mfma_f32_16x16x32_bf16 v[74:77], v[154:157], v[232:235], v[74:77]
	v_mfma_f32_16x16x32_bf16 v[78:81], v[142:145], v[228:231], v[78:81]
	v_mfma_f32_16x16x32_bf16 v[78:81], v[146:149], v[232:235], v[78:81]
	v_mfma_f32_16x16x32_bf16 v[82:85], v[134:137], v[228:231], v[82:85]
	v_mfma_f32_16x16x32_bf16 v[82:85], v[138:141], v[232:235], v[82:85]
	s_barrier
	s_add_i32 s4, s4, s24
	s_add_i32 m0, s4, 0xffffff80
	ds_read_b128 v[184:187], v188 offset:49152
	ds_read_b128 v[190:193], v188 offset:50176
	ds_read_b128 v[212:215], v188 offset:51200
	ds_read_b128 v[216:219], v188 offset:52224
	ds_read_b128 v[220:223], v188 offset:53248
	ds_read_b128 v[224:227], v188 offset:54272
	ds_read_b128 v[228:231], v188 offset:55296
	ds_read_b128 v[232:235], v188 offset:56320
	global_load_lds_dwordx4 v4, s[52:53] offset:128
	s_add_i32 m0, s4, 0x1f80
	s_add_u32 s22, s52, 0x160080
	s_addc_u32 s23, s53, 0
	s_add_i32 s4, s5, s24
	global_load_lds_dwordx4 v170, s[52:53] offset:128
	s_mov_b32 m0, s4
	s_nop 0
	global_load_lds_dwordx4 v4, s[22:23]
	s_add_i32 m0, s4, 0x2000
	s_nop 0
	global_load_lds_dwordx4 v170, s[22:23]
	s_add_i32 m0, s61, 0xffffff80
	s_nop 0
	global_load_lds_dwordx4 v2, s[54:55] offset:128
	s_add_i32 m0, s64, 0xffffff80
	s_nop 0
	global_load_lds_dwordx4 v168, s[54:55] offset:128
	s_waitcnt vmcnt(8)
	s_waitcnt lgkmcnt(0)
	s_barrier
	v_mfma_f32_16x16x32_bf16 v[58:61], v[134:137], v[184:187], v[58:61]
	v_mfma_f32_16x16x32_bf16 v[58:61], v[138:141], v[190:193], v[58:61]
	v_mfma_f32_16x16x32_bf16 v[54:57], v[142:145], v[184:187], v[54:57]
	v_mfma_f32_16x16x32_bf16 v[54:57], v[146:149], v[190:193], v[54:57]
	v_mfma_f32_16x16x32_bf16 v[66:69], v[150:153], v[184:187], v[66:69]
	v_mfma_f32_16x16x32_bf16 v[66:69], v[154:157], v[190:193], v[66:69]
	v_mfma_f32_16x16x32_bf16 v[62:65], v[176:179], v[184:187], v[62:65]
	v_mfma_f32_16x16x32_bf16 v[62:65], v[180:183], v[190:193], v[62:65]
	v_mfma_f32_16x16x32_bf16 v[38:41], v[176:179], v[212:215], v[38:41]
	v_mfma_f32_16x16x32_bf16 v[38:41], v[180:183], v[216:219], v[38:41]
	v_mfma_f32_16x16x32_bf16 v[42:45], v[150:153], v[212:215], v[42:45]
	v_mfma_f32_16x16x32_bf16 v[42:45], v[154:157], v[216:219], v[42:45]
	v_mfma_f32_16x16x32_bf16 v[46:49], v[142:145], v[212:215], v[46:49]
	v_mfma_f32_16x16x32_bf16 v[46:49], v[146:149], v[216:219], v[46:49]
	v_mfma_f32_16x16x32_bf16 v[50:53], v[134:137], v[212:215], v[50:53]
	v_mfma_f32_16x16x32_bf16 v[50:53], v[138:141], v[216:219], v[50:53]
	v_mfma_f32_16x16x32_bf16 v[34:37], v[134:137], v[220:223], v[34:37]
	v_mfma_f32_16x16x32_bf16 v[34:37], v[138:141], v[224:227], v[34:37]
	v_mfma_f32_16x16x32_bf16 v[30:33], v[142:145], v[220:223], v[30:33]
	v_mfma_f32_16x16x32_bf16 v[30:33], v[146:149], v[224:227], v[30:33]
	v_mfma_f32_16x16x32_bf16 v[26:29], v[150:153], v[220:223], v[26:29]
	v_mfma_f32_16x16x32_bf16 v[26:29], v[154:157], v[224:227], v[26:29]
	v_mfma_f32_16x16x32_bf16 v[22:25], v[176:179], v[220:223], v[22:25]
	v_mfma_f32_16x16x32_bf16 v[22:25], v[180:183], v[224:227], v[22:25]
	v_mfma_f32_16x16x32_bf16 v[6:9], v[176:179], v[228:231], v[6:9]
	v_mfma_f32_16x16x32_bf16 v[6:9], v[180:183], v[232:235], v[6:9]
	v_mfma_f32_16x16x32_bf16 v[10:13], v[150:153], v[228:231], v[10:13]
	v_mfma_f32_16x16x32_bf16 v[10:13], v[154:157], v[232:235], v[10:13]
	v_mfma_f32_16x16x32_bf16 v[14:17], v[142:145], v[228:231], v[14:17]
	v_mfma_f32_16x16x32_bf16 v[14:17], v[146:149], v[232:235], v[14:17]
	v_mfma_f32_16x16x32_bf16 v[18:21], v[134:137], v[228:231], v[18:21]
	v_mfma_f32_16x16x32_bf16 v[18:21], v[138:141], v[232:235], v[18:21]
	s_barrier
	s_add_i32 s20, s20, 2
	s_add_u32 s33, s33, 0x100
	s_addc_u32 s69, s69, 0
	s_cmpk_gt_u32 s20, 0x55
	s_mov_b64 s[22:23], s[50:51]
	s_cbranch_scc0 .LBB0_299
	s_and_b64 vcc, exec, s[46:47]
	s_cbranch_vccz .LBB0_302
	s_barrier
